# GLA scan chunk loop: LDS fragment reads batched in all three MFMA steps; store-aware vmcnt for the out-tile waves
# speedup vs baseline: 1.0146x; 1.0048x over previous
.LBB0_572:
	s_or_b64 exec, exec, vcc
	v_add_u32_e32 v185, -1, v185
	v_cmp_eq_u32_e32 vcc, -1, v185
	s_or_b64 s[42:43], vcc, s[42:43]
	s_mov_b32 s44, s46
	s_cmp_eq_u64 s[6:7], 0
	s_cbranch_scc1 .Lsc_nostore
	s_waitcnt vmcnt(19)
	v_mov_b32_e32 v46, v86
	v_mov_b32_e32 v47, v87
	v_mov_b32_e32 v48, v88
	v_mov_b32_e32 v49, v89
	s_waitcnt vmcnt(18)
	v_mov_b32_e32 v50, v78
	v_mov_b32_e32 v51, v79
	v_mov_b32_e32 v52, v80
	v_mov_b32_e32 v53, v81
	s_waitcnt vmcnt(17)
	v_mov_b32_e32 v38, v66
	v_mov_b32_e32 v39, v67
	v_mov_b32_e32 v40, v68
	v_mov_b32_e32 v41, v69
	s_waitcnt vmcnt(16)
	v_mov_b32_e32 v42, v62
	v_mov_b32_e32 v43, v63
	v_mov_b32_e32 v44, v64
	v_mov_b32_e32 v45, v65
	s_branch .Lsc_join
.Lsc_nostore:
	s_waitcnt vmcnt(3)
	v_mov_b32_e32 v46, v86
	v_mov_b32_e32 v47, v87
	v_mov_b32_e32 v48, v88
	v_mov_b32_e32 v49, v89
	s_waitcnt vmcnt(2)
	v_mov_b32_e32 v50, v78
	v_mov_b32_e32 v51, v79
	v_mov_b32_e32 v52, v80
	v_mov_b32_e32 v53, v81
	s_waitcnt vmcnt(1)
	v_mov_b32_e32 v38, v66
	v_mov_b32_e32 v39, v67
	v_mov_b32_e32 v40, v68
	v_mov_b32_e32 v41, v69
	s_waitcnt vmcnt(0)
	v_mov_b32_e32 v42, v62
	v_mov_b32_e32 v43, v63
	v_mov_b32_e32 v44, v64
	v_mov_b32_e32 v45, v65
.Lsc_join:
	ds_write_b128 v179, v[58:61] offset:28160
	ds_write_b128 v179, v[70:73] offset:32512
	ds_write_b128 v179, v[74:77] offset:36864
	ds_write_b128 v179, v[82:85] offset:41216
	ds_write_b128 v179, v[90:93] offset:45568
	ds_write_b128 v179, v[94:97] offset:49920
	ds_write_b128 v179, v[98:101] offset:54272
	ds_write_b128 v179, v[102:105] offset:58624
	s_andn2_b64 exec, exec, s[42:43]
	s_cbranch_execz .LBB0_577
.LBB0_573:
	s_add_i32 s46, s44, 1
	v_min_i32_e32 v20, s46, v181
	v_sub_u32_e32 v21, v181, v20
	v_cndmask_b32_e64 v20, v21, v20, s[18:19]
	v_lshl_add_u32 v20, v20, 6, v183
	v_ashrrev_i32_e32 v21, 31, v20
	v_lshl_add_u64 v[22:23], v[20:21], 1, v[206:207]
	global_load_dwordx4 v[54:57], v[22:23], off
	v_ashrrev_i32_e32 v22, 6, v20
	v_ashrrev_i32_e32 v23, 31, v22
	v_lshlrev_b64 v[24:25], 9, v[22:23]
	v_lshl_add_u64 v[24:25], v[208:209], 0, v[24:25]
	v_lshlrev_b64 v[20:21], 8, v[20:21]
	global_load_dword v187, v[24:25], off
	v_lshl_add_u64 v[24:25], v[210:211], 0, v[20:21]
	s_movk_i32 s45, 0x2000
	v_add_co_u32_e32 v26, vcc, s45, v24
	s_movk_i32 s47, 0x3000
	s_nop 0
	v_addc_co_u32_e32 v27, vcc, 0, v25, vcc
	global_load_dwordx4 v[58:61], v[24:25], off
	v_add_co_u32_e32 v24, vcc, s47, v24
	v_lshl_add_u64 v[20:21], v[212:213], 0, v[20:21]
	s_nop 0
	v_addc_co_u32_e32 v25, vcc, 0, v25, vcc
	global_load_dwordx4 v[70:73], v[26:27], off offset:-4096
	global_load_dwordx4 v[74:77], v[26:27], off
	global_load_dwordx4 v[82:85], v[24:25], off
	global_load_dwordx4 v[90:93], v[20:21], off
	v_add_co_u32_e32 v24, vcc, s45, v20
	v_add_u32_e32 v158, v163, v150
	s_nop 0
	v_addc_co_u32_e32 v25, vcc, 0, v21, vcc
	v_add_co_u32_e32 v20, vcc, s47, v20
	global_load_dwordx4 v[94:97], v[24:25], off offset:-4096
	global_load_dwordx4 v[98:101], v[24:25], off
	v_addc_co_u32_e32 v21, vcc, 0, v21, vcc
	global_load_dwordx4 v[102:105], v[20:21], off
	v_lshl_add_u64 v[20:21], v[2:3], 0, v[22:23]
	v_lshlrev_b64 v[20:21], 14, v[20:21]
	v_lshl_or_b32 v20, v198, 7, v20
	v_lshl_add_u64 v[20:21], v[152:153], 0, v[20:21]
	global_load_dwordx4 v[86:89], v[20:21], off
	global_load_dwordx4 v[78:81], v[20:21], off offset:32
	global_load_dwordx4 v[66:69], v[20:21], off offset:64
	global_load_dwordx4 v[62:65], v[20:21], off offset:96
	s_waitcnt lgkmcnt(0)
	s_barrier
	ds_read_b128 v[106:109], v173 offset:28160
	ds_read_b128 v[234:237], v158 offset:45568
	ds_read_b128 v[110:113], v173 offset:28192
	ds_read_b128 v[238:241], v158 offset:45600
	ds_read_b128 v[134:137], v173 offset:28224
	ds_read_b128 v[242:245], v158 offset:45632
	ds_read_b128 v[114:117], v173 offset:28256
	ds_read_b128 v[246:249], v158 offset:45664
	ds_read_b128 v[118:121], v173 offset:28288
	ds_read_b128 v[250:253], v158 offset:45696
	ds_read_b128 v[122:125], v173 offset:28320
	ds_read_b128 v[126:129], v173 offset:28352
	ds_read_b128 v[130:133], v173 offset:28384
	s_and_b32 s45, s44, 1
	s_mul_i32 s47, s45, 0x1200
	v_add_u32_e32 v189, s47, v154
	v_add3_u32 v189, v189, v165, v150
	s_waitcnt lgkmcnt(11)
	v_mfma_f32_32x32x16_bf16 v[20:35], v[106:109], v[234:237], 0
	ds_read_b128 v[234:237], v158 offset:45728
	s_waitcnt lgkmcnt(10)
	v_mfma_f32_32x32x16_bf16 v[20:35], v[110:113], v[238:241], v[20:35]
	ds_read_b128 v[238:241], v158 offset:45760
	s_waitcnt lgkmcnt(9)
	v_mfma_f32_32x32x16_bf16 v[20:35], v[134:137], v[242:245], v[20:35]
	ds_read_b128 v[242:245], v158 offset:45792
	s_waitcnt lgkmcnt(8)
	v_mfma_f32_32x32x16_bf16 v[20:35], v[114:117], v[246:249], v[20:35]
	s_waitcnt lgkmcnt(6)
	v_mfma_f32_32x32x16_bf16 v[20:35], v[118:121], v[250:253], v[20:35]
	s_waitcnt lgkmcnt(2)
	v_mfma_f32_32x32x16_bf16 v[20:35], v[122:125], v[234:237], v[20:35]
	s_waitcnt lgkmcnt(1)
	v_mfma_f32_32x32x16_bf16 v[20:35], v[126:129], v[238:241], v[20:35]
	s_waitcnt lgkmcnt(0)
	v_mfma_f32_32x32x16_bf16 v[20:35], v[130:133], v[242:245], v[20:35]
	s_nop 11
	v_cndmask_b32_e64 v20, 0, v20, s[78:79]
	v_cndmask_b32_e64 v21, 0, v21, s[80:81]
	v_bfe_u32 v158, v20, 16, 1
	v_cndmask_b32_e64 v22, 0, v22, s[82:83]
	v_bfe_u32 v159, v21, 16, 1
	v_add3_u32 v20, v20, v158, s73
	v_add3_u32 v21, v21, v159, s73
	ds_write_b16_d16_hi v175, v20 offset:8704
	ds_write_b16_d16_hi v175, v21 offset:8848
	v_bfe_u32 v20, v22, 16, 1
	v_add3_u32 v20, v22, v20, s73
	ds_write_b16_d16_hi v175, v20 offset:8992
	v_cndmask_b32_e64 v20, 0, v23, s[84:85]
	v_bfe_u32 v21, v20, 16, 1
	v_add3_u32 v20, v20, v21, s73
	ds_write_b16_d16_hi v175, v20 offset:9136
	v_cndmask_b32_e64 v20, 0, v24, s[86:87]
	v_bfe_u32 v21, v20, 16, 1
	v_add3_u32 v20, v20, v21, s73
	ds_write_b16_d16_hi v175, v20 offset:9856
	v_cndmask_b32_e64 v20, 0, v25, s[88:89]
	v_bfe_u32 v21, v20, 16, 1
	v_add3_u32 v20, v20, v21, s73
	ds_write_b16_d16_hi v175, v20 offset:10000
	v_cndmask_b32_e64 v20, 0, v26, s[90:91]
	v_bfe_u32 v21, v20, 16, 1
	v_add3_u32 v20, v20, v21, s73
	ds_write_b16_d16_hi v175, v20 offset:10144
	v_cndmask_b32_e64 v20, 0, v27, s[92:93]
	v_bfe_u32 v21, v20, 16, 1
	v_add3_u32 v20, v20, v21, s73
	ds_write_b16_d16_hi v175, v20 offset:10288
	v_cndmask_b32_e64 v20, 0, v28, s[94:95]
	v_bfe_u32 v21, v20, 16, 1
	v_add3_u32 v20, v20, v21, s73
	ds_write_b16_d16_hi v175, v20 offset:11008
	v_cndmask_b32_e64 v20, 0, v29, s[96:97]
	v_bfe_u32 v21, v20, 16, 1
	v_add3_u32 v20, v20, v21, s73
	ds_write_b16_d16_hi v175, v20 offset:11152
	v_cndmask_b32_e64 v20, 0, v30, s[16:17]
	v_bfe_u32 v21, v20, 16, 1
	v_add3_u32 v20, v20, v21, s73
	ds_write_b16_d16_hi v175, v20 offset:11296
	v_cndmask_b32_e64 v20, 0, v31, s[8:9]
	v_bfe_u32 v21, v20, 16, 1
	v_add3_u32 v20, v20, v21, s73
	ds_write_b16_d16_hi v175, v20 offset:11440
	v_cndmask_b32_e64 v20, 0, v32, s[0:1]
	v_bfe_u32 v21, v20, 16, 1
	v_add3_u32 v20, v20, v21, s73
	ds_write_b16_d16_hi v175, v20 offset:12160
	v_cndmask_b32_e64 v20, 0, v33, s[10:11]
	v_bfe_u32 v21, v20, 16, 1
	v_add3_u32 v20, v20, v21, s73
	ds_write_b16_d16_hi v175, v20 offset:12304
	v_cndmask_b32_e64 v20, 0, v34, s[12:13]
	v_bfe_u32 v21, v20, 16, 1
	v_add3_u32 v20, v20, v21, s73
	ds_write_b16_d16_hi v175, v20 offset:12448
	v_cndmask_b32_e64 v20, 0, v35, s[14:15]
	v_bfe_u32 v21, v20, 16, 1
	v_add3_u32 v20, v20, v21, s73
	ds_write_b16_d16_hi v175, v20 offset:12592
	s_waitcnt lgkmcnt(0)
	s_barrier
	s_and_saveexec_b64 vcc, s[6:7]
	s_cbranch_execz .LBB0_575
	v_mov_b32_e32 v20, s44
	v_cndmask_b32_e64 v20, v185, v20, s[18:19]
	v_lshl_add_u32 v230, v20, 6, v183
	ds_read_b128 v[234:237], v169
	ds_read_b128 v[238:241], v169 offset:32
	ds_read_b128 v[242:245], v169 offset:64
	ds_read_b128 v[246:249], v169 offset:96
	ds_read_b128 v[250:253], v169 offset:128
	ds_read_b128 v[158:161], v169 offset:160
	v_ashrrev_i32_e32 v231, 31, v230
	s_waitcnt lgkmcnt(5)
	v_mfma_f32_32x32x16_bf16 v[20:35], v[106:109], v[234:237], 0
	ds_read_b128 v[106:109], v169 offset:192
	ds_read_b128 v[234:237], v177 offset:8704
	s_waitcnt lgkmcnt(6)
	v_mfma_f32_32x32x16_bf16 v[20:35], v[110:113], v[238:241], v[20:35]
	ds_read_b128 v[110:113], v169 offset:224
	ds_read_b128 v[238:241], v189 offset:17920
	s_waitcnt lgkmcnt(7)
	v_mfma_f32_32x32x16_bf16 v[20:35], v[134:137], v[242:245], v[20:35]
	ds_read_b128 v[242:245], v177 offset:8736
	ds_read_b128 v[134:137], v189 offset:17952
	s_waitcnt lgkmcnt(8)
	v_mfma_f32_32x32x16_bf16 v[20:35], v[114:117], v[246:249], v[20:35]
	ds_read_b128 v[246:249], v177 offset:8768
	ds_read_b128 v[114:117], v189 offset:17984
	s_waitcnt lgkmcnt(9)
	v_mfma_f32_32x32x16_bf16 v[20:35], v[118:121], v[250:253], v[20:35]
	ds_read_b128 v[250:253], v177 offset:8800
	ds_read_b128 v[118:121], v189 offset:18016
	s_waitcnt lgkmcnt(10)
	v_mfma_f32_32x32x16_bf16 v[20:35], v[122:125], v[158:161], v[20:35]
	s_waitcnt lgkmcnt(9)
	v_mfma_f32_32x32x16_bf16 v[20:35], v[126:129], v[106:109], v[20:35]
	s_waitcnt lgkmcnt(7)
	v_mfma_f32_32x32x16_bf16 v[20:35], v[130:133], v[110:113], v[20:35]
	s_waitcnt lgkmcnt(6)
	v_mfma_f32_32x32x16_bf16 v[20:35], v[234:237], v[238:241], v[20:35]
	s_waitcnt lgkmcnt(4)
	v_mfma_f32_32x32x16_bf16 v[20:35], v[242:245], v[134:137], v[20:35]
	s_waitcnt lgkmcnt(2)
	v_mfma_f32_32x32x16_bf16 v[20:35], v[246:249], v[114:117], v[20:35]
	s_waitcnt lgkmcnt(0)
	v_mfma_f32_32x32x16_bf16 v[20:35], v[250:253], v[118:121], v[20:35]
	v_lshl_add_u64 v[106:107], v[214:215], 0, v[230:231]
	v_mov_b32_e32 v109, v107
	s_nop 9
	v_bfe_u32 v108, v20, 16, 1
	v_add3_u32 v20, v20, v108, s73
	v_or_b32_e32 v108, v106, v162
	v_lshlrev_b64 v[108:109], 11, v[108:109]
	v_lshl_add_u64 v[108:109], v[216:217], 0, v[108:109]
	global_store_short_d16_hi v[108:109], v20, off
	v_bfe_u32 v20, v21, 16, 1
	v_add3_u32 v108, v21, v20, s73
	v_or_b32_e32 v20, v106, v168
	v_mov_b32_e32 v21, v107
	v_lshlrev_b64 v[20:21], 11, v[20:21]
	v_lshl_add_u64 v[20:21], v[216:217], 0, v[20:21]
	global_store_short_d16_hi v[20:21], v108, off
	v_bfe_u32 v20, v22, 16, 1
	v_add3_u32 v22, v22, v20, s73
	v_or_b32_e32 v20, v106, v170
	v_mov_b32_e32 v21, v107
	v_lshlrev_b64 v[20:21], 11, v[20:21]
	v_lshl_add_u64 v[20:21], v[216:217], 0, v[20:21]
	global_store_short_d16_hi v[20:21], v22, off
	v_bfe_u32 v20, v23, 16, 1
	v_add3_u32 v22, v23, v20, s73
	v_or_b32_e32 v20, v106, v172
	v_mov_b32_e32 v21, v107
	v_lshlrev_b64 v[20:21], 11, v[20:21]
	v_lshl_add_u64 v[20:21], v[216:217], 0, v[20:21]
	global_store_short_d16_hi v[20:21], v22, off
	v_bfe_u32 v20, v24, 16, 1
	v_add3_u32 v22, v24, v20, s73
	v_or_b32_e32 v20, v106, v174
	v_mov_b32_e32 v21, v107
	v_lshlrev_b64 v[20:21], 11, v[20:21]
	v_lshl_add_u64 v[20:21], v[216:217], 0, v[20:21]
	global_store_short_d16_hi v[20:21], v22, off
	v_bfe_u32 v20, v25, 16, 1
	v_add3_u32 v22, v25, v20, s73
	v_or_b32_e32 v20, v106, v176
	v_mov_b32_e32 v21, v107
	v_lshlrev_b64 v[20:21], 11, v[20:21]
	v_lshl_add_u64 v[20:21], v[216:217], 0, v[20:21]
	global_store_short_d16_hi v[20:21], v22, off
	v_bfe_u32 v20, v26, 16, 1
	v_add3_u32 v22, v26, v20, s73
	v_or_b32_e32 v20, v106, v178
	v_mov_b32_e32 v21, v107
	v_lshlrev_b64 v[20:21], 11, v[20:21]
	v_lshl_add_u64 v[20:21], v[216:217], 0, v[20:21]
	global_store_short_d16_hi v[20:21], v22, off
	v_bfe_u32 v20, v27, 16, 1
	v_add3_u32 v22, v27, v20, s73
	v_or_b32_e32 v20, v106, v180
	v_mov_b32_e32 v21, v107
	v_lshlrev_b64 v[20:21], 11, v[20:21]
	v_lshl_add_u64 v[20:21], v[216:217], 0, v[20:21]
	global_store_short_d16_hi v[20:21], v22, off
	v_bfe_u32 v20, v28, 16, 1
	v_add3_u32 v22, v28, v20, s73
	v_or_b32_e32 v20, v106, v182
	v_mov_b32_e32 v21, v107
	v_lshlrev_b64 v[20:21], 11, v[20:21]
	v_lshl_add_u64 v[20:21], v[216:217], 0, v[20:21]
	global_store_short_d16_hi v[20:21], v22, off
	v_bfe_u32 v20, v29, 16, 1
	v_add3_u32 v22, v29, v20, s73
	v_or_b32_e32 v20, v106, v184
	v_mov_b32_e32 v21, v107
	v_lshlrev_b64 v[20:21], 11, v[20:21]
	v_lshl_add_u64 v[20:21], v[216:217], 0, v[20:21]
	global_store_short_d16_hi v[20:21], v22, off
	v_bfe_u32 v20, v30, 16, 1
	v_add3_u32 v22, v30, v20, s73
	v_or_b32_e32 v20, v106, v186
	v_mov_b32_e32 v21, v107
	v_lshlrev_b64 v[20:21], 11, v[20:21]
	v_lshl_add_u64 v[20:21], v[216:217], 0, v[20:21]
	global_store_short_d16_hi v[20:21], v22, off
	v_bfe_u32 v20, v31, 16, 1
	v_add3_u32 v22, v31, v20, s73
	v_or_b32_e32 v20, v106, v188
	v_mov_b32_e32 v21, v107
	v_lshlrev_b64 v[20:21], 11, v[20:21]
	v_lshl_add_u64 v[20:21], v[216:217], 0, v[20:21]
	global_store_short_d16_hi v[20:21], v22, off
	v_bfe_u32 v20, v32, 16, 1
	v_add3_u32 v22, v32, v20, s73
	v_or_b32_e32 v20, v106, v190
	v_mov_b32_e32 v21, v107
	v_lshlrev_b64 v[20:21], 11, v[20:21]
	v_lshl_add_u64 v[20:21], v[216:217], 0, v[20:21]
	global_store_short_d16_hi v[20:21], v22, off
	v_bfe_u32 v20, v33, 16, 1
	v_add3_u32 v22, v33, v20, s73
	v_or_b32_e32 v20, v106, v192
	v_mov_b32_e32 v21, v107
	v_lshlrev_b64 v[20:21], 11, v[20:21]
	v_lshl_add_u64 v[20:21], v[216:217], 0, v[20:21]
	global_store_short_d16_hi v[20:21], v22, off
	v_bfe_u32 v20, v34, 16, 1
	v_add3_u32 v22, v34, v20, s73
	v_or_b32_e32 v20, v106, v194
	v_mov_b32_e32 v21, v107
	v_lshlrev_b64 v[20:21], 11, v[20:21]
	v_lshl_add_u64 v[20:21], v[216:217], 0, v[20:21]
	global_store_short_d16_hi v[20:21], v22, off
	v_bfe_u32 v20, v35, 16, 1
	v_or_b32_e32 v106, v106, v196
	v_add3_u32 v22, v35, v20, s73
	v_lshlrev_b64 v[20:21], 11, v[106:107]
	v_lshl_add_u64 v[20:21], v[216:217], 0, v[20:21]
	global_store_short_d16_hi v[20:21], v22, off
.LBB0_575:
	s_or_b64 exec, exec, vcc
	v_lshl_add_u32 v34, s45, 9, v171
	v_add_u32_e32 v24, 0x6a20, v34
	v_add_u32_e32 v26, 0x6a28, v34
	ds_read_b128 v[20:23], v34 offset:27136
	ds_read2_b32 v[24:25], v24 offset1:1
	ds_read2_b32 v[26:27], v26 offset1:1
	v_add_u32_e32 v28, 0x6a40, v34
	v_add_u32_e32 v30, 0x6a48, v34
	v_add_u32_e32 v32, 0x6a60, v34
	v_add_u32_e32 v34, 0x6a68, v34
	ds_read2_b32 v[28:29], v28 offset1:1
	ds_read2_b32 v[30:31], v30 offset1:1
	ds_read2_b32 v[32:33], v32 offset1:1
	ds_read2_b32 v[34:35], v34 offset1:1
	s_waitcnt lgkmcnt(6)
	v_pk_mul_f32 v[6:7], v[6:7], v[22:23]
	s_waitcnt lgkmcnt(4)
	v_pk_mul_f32 v[10:11], v[10:11], v[26:27]
	v_pk_mul_f32 v[8:9], v[8:9], v[24:25]
	v_pk_mul_f32 v[4:5], v[4:5], v[20:21]
	ds_read_b128 v[20:23], v189 offset:17920
	ds_read_b128 v[24:27], v189 offset:17952
	ds_read_b128 v[234:237], v189 offset:17984
	ds_read_b128 v[238:241], v189 offset:18016
	s_waitcnt lgkmcnt(4)
	v_pk_mul_f32 v[18:19], v[18:19], v[34:35]
	v_pk_mul_f32 v[16:17], v[16:17], v[32:33]
	v_pk_mul_f32 v[14:15], v[14:15], v[30:31]
	v_pk_mul_f32 v[12:13], v[12:13], v[28:29]
	s_and_b32 s44, s46, 1
	s_mul_i32 s45, s44, 0x1200
	s_waitcnt lgkmcnt(3)
	v_mfma_f32_32x32x16_bf16 v[4:19], v[46:49], v[20:23], v[4:19]
	s_waitcnt lgkmcnt(2)
	v_mfma_f32_32x32x16_bf16 v[4:19], v[50:53], v[24:27], v[4:19]
	s_waitcnt lgkmcnt(1)
	v_mfma_f32_32x32x16_bf16 v[4:19], v[38:41], v[234:237], v[4:19]
	s_waitcnt lgkmcnt(0)
	s_barrier
	v_mfma_f32_32x32x16_bf16 v[4:19], v[42:45], v[238:241], v[4:19]
	s_nop 11
	v_cvt_pk_bf16_f32 v20, v4, v5
	v_cvt_pk_bf16_f32 v21, v6, v7
	v_cvt_pk_bf16_f32 v22, v8, v9
	v_cvt_pk_bf16_f32 v23, v10, v11
	ds_write2_b64 v155, v[20:21], v[22:23] offset1:2
	v_cvt_pk_bf16_f32 v20, v12, v13
	v_cvt_pk_bf16_f32 v21, v14, v15
	v_cvt_pk_bf16_f32 v22, v16, v17
	v_cvt_pk_bf16_f32 v23, v18, v19
	ds_write2_b64 v155, v[20:21], v[22:23] offset0:4 offset1:6
	v_add_u32_e32 v20, s45, v156
	s_cmp_eq_u64 s[6:7], 0
	s_cbranch_scc1 .Lsc_w13
	s_waitcnt vmcnt(29)
	s_branch .Lsc_w13j
.Lsc_w13:
	s_waitcnt vmcnt(13)
.Lsc_w13j:
	ds_write_b128 v20, v[54:57] offset:17920
	s_and_saveexec_b64 vcc, s[4:5]
	s_cbranch_execz .LBB0_572
	v_lshl_add_u32 v20, s44, 9, v157
	s_cmp_eq_u64 s[6:7], 0
	s_cbranch_scc1 .Lsc_w12
	s_waitcnt vmcnt(28)
	s_branch .Lsc_w12j
.Lsc_w12:
	s_waitcnt vmcnt(12)
.Lsc_w12j:
	ds_write_b32 v20, v187 offset:27136
	s_branch .LBB0_572
